# code placement: attention loop head pinned to a 64-byte boundary (0xFE40) with s_nop padding before the pass setup
# baseline (speedup 1.0000x reference)
; #define WAITBAR(N) asm volatile("s_waitcnt vmcnt(" #N ") lgkmcnt(0)\n\ts_barrier" ::: "memory")
; __device__ __forceinline__ void attn_unit(int b, int h, int qb, const bf16_t* __restrict__ proj, const float* __restrict__ btab, float lam, float outscale,
;                                           const float* __restrict__ gain, float* o1scr, bf16_t* merged, LAS char* lds) {
;     ...
;         const bf16_t* Qw = proj + (rowbase + qw + r32) * LD + OQ + hq * 64 + hi * 8;
;         float m_reg = -1e30f, l_reg = 0; f32x16 o[4]; bf16x8 qr[4];
; #pragma unroll
;         for (int d0 = 0; d0 < 4; ++d0) { o[d0] = f32x16{}; qr[d0] = *(const bf16x8*)(Qw + d0 * 16); }
;     ...
;         f32x16 pA0, pA1, pB0, pB1; float mnA, mnB, alA, alB, bo; bf16x8 pa0, pa1, pa2, pa3; constexpr int NT = T / 64;
;         asm volatile("s_waitcnt vmcnt(0) lgkmcnt(0)" ::: "memory"); __syncthreads();
;         DMA_TILE(0, 0); DMA_TILE(1, 1);
;         WAITBAR(3);
.LBB0_187:
	s_or_b32 s24, s6, s48
	s_lshl_b64 s[2:3], s[24:25], 1
	v_lshl_add_u64 v[2:3], v[190:191], 0, s[2:3]
	s_add_u32 s2, s36, s2
	s_addc_u32 s3, s37, s3
	global_load_dwordx4 v[142:145], v[2:3], off
	global_load_dwordx4 v[138:141], v[2:3], off offset:32
	global_load_dwordx4 v[134:137], v[2:3], off offset:64
	global_load_dwordx4 v[130:133], v[2:3], off offset:96
	s_nop 0
	s_nop 0
	s_nop 0
	s_nop 0
	s_nop 0
	s_nop 0
	s_nop 0
	s_nop 0
	s_nop 0
	s_nop 0
	s_nop 0
	s_nop 0
	s_nop 0
	s_nop 0
	v_lshl_add_u64 v[184:185], s[2:3], 0, v[186:187]
	s_xor_b64 s[2:3], s[0:1], -1
	s_mov_b64 s[6:7], 0x800
	v_lshl_add_u64 v[184:185], v[184:185], 0, s[6:7]
	v_mov_b64_e32 v[250:251], v[192:193]
	v_mov_b64_e32 v[246:247], v[194:195]
	s_mov_b32 s6, 0xc8000
	s_mov_b32 s7, 0
	v_readfirstlane_b32 s67, v222
	v_add_u32_e32 v239, v226, v227
	v_add_u32_e32 v240, v226, v228
	v_add_u32_e32 v241, v226, v229
	v_add_u32_e32 v242, v226, v230
	s_lshr_b32 s67, s67, 8
	v_add_u32_e32 v239, 0x14000, v239
	v_add_u32_e32 v240, 0x14000, v240
	v_add_u32_e32 v241, 0x14000, v241
	v_add_u32_e32 v242, 0x14000, v242
	v_mov_b32_e32 v243, v215
	v_bfe_u32 v244, v222, 4, 1
	v_bfe_u32 v249, v222, 6, 1
	v_sub_u32_e32 v244, v249, v244
	v_mul_i32_i24_e32 v244, 0xc800, v244
	v_ashrrev_i32_e32 v245, 31, v244
	v_lshl_add_u64 v[250:251], v[250:251], 0, v[244:245]
	v_lshl_add_u64 v[246:247], v[246:247], 0, v[244:245]
	v_mov_b32_e32 v2, 0
	v_mov_b32_e32 v3, 0
	v_mov_b32_e32 v4, 0
	v_mov_b32_e32 v5, 0
	v_mov_b32_e32 v6, 0
	v_mov_b32_e32 v7, 0
	v_mov_b32_e32 v8, 0
	v_mov_b32_e32 v9, 0
	v_mov_b32_e32 v10, 0
	v_mov_b32_e32 v11, 0
	v_mov_b32_e32 v12, 0
	v_mov_b32_e32 v13, 0
	v_mov_b32_e32 v14, 0
	v_mov_b32_e32 v15, 0
	v_mov_b32_e32 v16, 0
	v_mov_b32_e32 v17, 0
	v_mov_b32_e32 v18, 0
	v_mov_b32_e32 v19, 0
	v_mov_b32_e32 v20, 0
	v_mov_b32_e32 v21, 0
	v_mov_b32_e32 v22, 0
	v_mov_b32_e32 v23, 0
	v_mov_b32_e32 v24, 0
	v_mov_b32_e32 v25, 0
	v_mov_b32_e32 v26, 0
	v_mov_b32_e32 v27, 0
	v_mov_b32_e32 v28, 0
	v_mov_b32_e32 v29, 0
	v_mov_b32_e32 v30, 0
	v_mov_b32_e32 v31, 0
	v_mov_b32_e32 v32, 0
	v_mov_b32_e32 v33, 0
	v_mov_b32_e32 v34, 0
	v_mov_b32_e32 v35, 0
	v_mov_b32_e32 v36, 0
	v_mov_b32_e32 v37, 0
	v_mov_b32_e32 v38, 0
	v_mov_b32_e32 v39, 0
	v_mov_b32_e32 v40, 0
	v_mov_b32_e32 v41, 0
	v_mov_b32_e32 v42, 0
	v_mov_b32_e32 v43, 0
	v_mov_b32_e32 v44, 0
	v_mov_b32_e32 v45, 0
	v_mov_b32_e32 v46, 0
	v_mov_b32_e32 v47, 0
	v_mov_b32_e32 v48, 0
	v_mov_b32_e32 v49, 0
	v_mov_b32_e32 v50, 0
	v_mov_b32_e32 v51, 0
	v_mov_b32_e32 v52, 0
	v_mov_b32_e32 v53, 0
	v_mov_b32_e32 v54, 0
	v_mov_b32_e32 v55, 0
	v_mov_b32_e32 v56, 0
	v_mov_b32_e32 v57, 0
	v_mov_b32_e32 v58, 0
	v_mov_b32_e32 v59, 0
	v_mov_b32_e32 v60, 0
	v_mov_b32_e32 v61, 0
	v_mov_b32_e32 v62, 0
	v_mov_b32_e32 v63, 0
	v_mov_b32_e32 v64, 0
	v_mov_b32_e32 v65, 0
	v_mov_b32_e32 v238, 0
	v_add_u32_e32 v245, 0xffffff00, v235
	s_sub_i32 s65, s78, 0x80
	s_mov_b32 s40, 0
	s_waitcnt lgkmcnt(0)
	s_barrier
	s_mov_b32 s24, 0
	s_lshl_b32 s12, s24, 13
	s_add_i32 s12, s12, s66
	s_lshl_b32 s13, s24, 14
	s_add_i32 s13, s13, s74
	s_add_i32 m0, s12, 0x14000
	s_nop 0
	global_load_lds_dwordx4 v[184:185], off
	s_mov_b32 m0, s13
	v_lshl_add_u64 v[184:185], v[184:185], 0, s[6:7]
	global_load_lds_dwordx4 v[250:251], off
	s_add_i32 m0, s13, 0x400
	v_lshl_add_u64 v[250:251], v[250:251], 0, s[6:7]
	global_load_lds_dwordx4 v[246:247], off
	v_lshl_add_u64 v[246:247], v[246:247], 0, s[6:7]
	s_mov_b32 s24, 1
	s_lshl_b32 s12, s24, 13
	s_add_i32 s12, s12, s66
	s_lshl_b32 s13, s24, 14
	s_add_i32 s13, s13, s74
	s_add_i32 m0, s12, 0x14000
	s_nop 0
	global_load_lds_dwordx4 v[184:185], off
	s_mov_b32 m0, s13
	v_lshl_add_u64 v[184:185], v[184:185], 0, s[6:7]
	global_load_lds_dwordx4 v[250:251], off
	s_add_i32 m0, s13, 0x400
	v_lshl_add_u64 v[250:251], v[250:251], 0, s[6:7]
	global_load_lds_dwordx4 v[246:247], off
	v_lshl_add_u64 v[246:247], v[246:247], 0, s[6:7]
	s_waitcnt vmcnt(3)
	s_barrier
	s_cmp_eq_u32 s67, 0
	s_cbranch_scc1 .Lat_enter
	s_barrier
	s_setprio 1
